# v62 + SSD loop 64-bit addresses as s_mov_b64 vcc,literal + v_lshl_add_u64 (2 slots) instead of v_add_co/s_nop/v_addc (3)
# speedup vs baseline: 1.0103x; 1.0103x over previous
; __device__ __forceinline__ unsigned pk2(float lo, float hi) { unsigned r; asm("v_cvt_pk_bf16_f32 %0, %1, %2" : "=v"(r) : "v"(lo), "v"(hi)); return r; }
; __device__ __forceinline__ float silu_f(float v) { return v * __builtin_amdgcn_rcpf(1.f + __expf(-v)); }
; __device__ __forceinline__ void conv_rows(const u32x4 (&rawp)[5], const float* wl, float (&o0)[8], float (&o1)[8]) {
;     float raw[5][8];
; #pragma unroll
;     for (int q = 0; q < 5; ++q) unpack8(rawp[q], raw[q]);
; #pragma unroll
;     for (int h = 0; h < 2; ++h) {
;         const f32x4 bv = *(const f32x4*)(wl + 4 * 128 + h * 4);
;         f32x4 a0 = bv, a1 = bv;
; #pragma unroll
;         for (int k = 0; k < 4; ++k) { const f32x4 wv = *(const f32x4*)(wl + k * 128 + h * 4);
; #pragma unroll
;             for (int i = 0; i < 4; ++i) { a0[i] += wv[i] * raw[k][h * 4 + i]; a1[i] += wv[i] * raw[k + 1][h * 4 + i]; } }
; #pragma unroll
;         for (int i = 0; i < 4; ++i) { o0[h * 4 + i] = silu_f(a0[i]); o1[h * 4 + i] = silu_f(a1[i]); }
;         __builtin_amdgcn_sched_barrier(0);
;     }
; }
; __device__ __forceinline__ void phase_ssd(const Params& p, uchar* sm, int j, bf16_t* zx, const float* dtraw, float* ssqb) {
;     ...
;             conv_rows(rx, wlx, xo0, xo1);
;             __builtin_amdgcn_sched_barrier(0);
; #pragma unroll
;             for (int i = 0; i < 8; ++i) *(unsigned*)(sm + L_XT + (c8 * 8 + i) * RS_T + ((lp ^ swz) * 4)) = pk2(xo0[i], xo1[i]);
.LBB0_466:
	ds_read_b128 v[132:135], v187 offset:2048
	ds_read_b128 v[96:99], v187 offset:0
	ds_read_b128 v[120:123], v187 offset:512
	ds_read_b128 v[124:127], v187 offset:1024
	ds_read_b128 v[128:131], v187 offset:1536
	s_nop 0
	v_lshlrev_b32_e32 v100, 16, v4
	v_and_b32_e32 v101, 0xffff0000, v4
	v_lshlrev_b32_e32 v118, 16, v5
	v_and_b32_e32 v119, 0xffff0000, v5
	s_waitcnt lgkmcnt(3)
	v_pk_fma_f32 v[144:145], v[96:97], v[100:101], v[132:133]
	v_pk_fma_f32 v[178:179], v[98:99], v[118:119], v[134:135]
	v_lshlrev_b32_e32 v100, 16, v8
	v_and_b32_e32 v101, 0xffff0000, v8
	v_lshlrev_b32_e32 v118, 16, v9
	v_and_b32_e32 v119, 0xffff0000, v9
	s_waitcnt lgkmcnt(2)
	v_pk_fma_f32 v[144:145], v[120:121], v[100:101], v[144:145]
	v_pk_fma_f32 v[178:179], v[122:123], v[118:119], v[178:179]
	v_pk_fma_f32 v[180:181], v[96:97], v[100:101], v[132:133]
	v_pk_fma_f32 v[230:231], v[98:99], v[118:119], v[134:135]
	v_lshlrev_b32_e32 v100, 16, v12
	v_and_b32_e32 v101, 0xffff0000, v12
	v_lshlrev_b32_e32 v118, 16, v13
	v_and_b32_e32 v119, 0xffff0000, v13
	s_waitcnt lgkmcnt(1)
	v_pk_fma_f32 v[144:145], v[124:125], v[100:101], v[144:145]
	v_pk_fma_f32 v[178:179], v[126:127], v[118:119], v[178:179]
	v_pk_fma_f32 v[180:181], v[120:121], v[100:101], v[180:181]
	v_pk_fma_f32 v[230:231], v[122:123], v[118:119], v[230:231]
	v_lshlrev_b32_e32 v100, 16, v16
	v_and_b32_e32 v101, 0xffff0000, v16
	v_lshlrev_b32_e32 v118, 16, v17
	v_and_b32_e32 v119, 0xffff0000, v17
	s_waitcnt lgkmcnt(0)
	v_pk_fma_f32 v[144:145], v[128:129], v[100:101], v[144:145]
	v_pk_fma_f32 v[178:179], v[130:131], v[118:119], v[178:179]
	v_pk_fma_f32 v[180:181], v[124:125], v[100:101], v[180:181]
	v_pk_fma_f32 v[230:231], v[126:127], v[118:119], v[230:231]
	v_lshlrev_b32_e32 v100, 16, v24
	v_and_b32_e32 v101, 0xffff0000, v24
	v_lshlrev_b32_e32 v118, 16, v25
	v_and_b32_e32 v119, 0xffff0000, v25
	v_pk_fma_f32 v[180:181], v[128:129], v[100:101], v[180:181]
	v_pk_fma_f32 v[230:231], v[130:131], v[118:119], v[230:231]
	v_pk_mul_f32 v[96:97], v[144:145], s[98:99]
	v_pk_mul_f32 v[98:99], v[178:179], s[98:99]
	v_pk_mul_f32 v[120:121], v[180:181], s[98:99]
	v_pk_mul_f32 v[122:123], v[230:231], s[98:99]
	v_exp_f32_e32 v96, v96
	v_exp_f32_e32 v97, v97
	v_exp_f32_e32 v98, v98
	v_exp_f32_e32 v99, v99
	v_exp_f32_e32 v120, v120
	v_exp_f32_e32 v121, v121
	v_exp_f32_e32 v122, v122
	v_exp_f32_e32 v123, v123
	v_pk_add_f32 v[96:97], v[96:97], s[100:101]
	v_pk_add_f32 v[98:99], v[98:99], s[100:101]
	v_pk_add_f32 v[120:121], v[120:121], s[100:101]
	v_pk_add_f32 v[122:123], v[122:123], s[100:101]
	ds_read_b128 v[132:135], v187 offset:2064
	ds_read_b128 v[112:115], v187 offset:16
	v_rcp_f32_e32 v96, v96
	v_rcp_f32_e32 v97, v97
	v_rcp_f32_e32 v98, v98
	ds_read_b128 v[232:235], v187 offset:528
	v_rcp_f32_e32 v99, v99
	v_rcp_f32_e32 v120, v120
	v_rcp_f32_e32 v121, v121
	v_rcp_f32_e32 v122, v122
	ds_read_b128 v[124:127], v187 offset:1040
	v_rcp_f32_e32 v123, v123
	v_pk_mul_f32 v[104:105], v[144:145], v[96:97]
	v_pk_mul_f32 v[106:107], v[178:179], v[98:99]
	v_pk_mul_f32 v[102:103], v[180:181], v[120:121]
	ds_read_b128 v[128:131], v187 offset:1552
	v_pk_mul_f32 v[108:109], v[230:231], v[122:123]
	v_lshlrev_b32_e32 v100, 16, v6
	v_and_b32_e32 v101, 0xffff0000, v6
	v_lshlrev_b32_e32 v118, 16, v7
	v_and_b32_e32 v119, 0xffff0000, v7
	s_waitcnt lgkmcnt(3)
	v_pk_fma_f32 v[144:145], v[112:113], v[100:101], v[132:133]
	v_pk_fma_f32 v[178:179], v[114:115], v[118:119], v[134:135]
	v_lshlrev_b32_e32 v100, 16, v10
	v_and_b32_e32 v101, 0xffff0000, v10
	v_lshlrev_b32_e32 v118, 16, v11
	v_and_b32_e32 v119, 0xffff0000, v11
	s_waitcnt lgkmcnt(2)
	v_pk_fma_f32 v[144:145], v[232:233], v[100:101], v[144:145]
	v_pk_fma_f32 v[178:179], v[234:235], v[118:119], v[178:179]
	v_pk_fma_f32 v[180:181], v[112:113], v[100:101], v[132:133]
	v_pk_fma_f32 v[230:231], v[114:115], v[118:119], v[134:135]
	v_lshlrev_b32_e32 v100, 16, v14
	v_and_b32_e32 v101, 0xffff0000, v14
	v_lshlrev_b32_e32 v118, 16, v15
	v_and_b32_e32 v119, 0xffff0000, v15
	s_waitcnt lgkmcnt(1)
	v_pk_fma_f32 v[144:145], v[124:125], v[100:101], v[144:145]
	v_pk_fma_f32 v[178:179], v[126:127], v[118:119], v[178:179]
	v_pk_fma_f32 v[180:181], v[232:233], v[100:101], v[180:181]
	v_pk_fma_f32 v[230:231], v[234:235], v[118:119], v[230:231]
	v_lshlrev_b32_e32 v100, 16, v18
	v_and_b32_e32 v101, 0xffff0000, v18
	v_lshlrev_b32_e32 v118, 16, v19
	v_and_b32_e32 v119, 0xffff0000, v19
	s_waitcnt lgkmcnt(0)
	v_pk_fma_f32 v[144:145], v[128:129], v[100:101], v[144:145]
	v_pk_fma_f32 v[178:179], v[130:131], v[118:119], v[178:179]
	v_pk_fma_f32 v[180:181], v[124:125], v[100:101], v[180:181]
	v_pk_fma_f32 v[230:231], v[126:127], v[118:119], v[230:231]
	v_lshlrev_b32_e32 v100, 16, v26
	v_and_b32_e32 v101, 0xffff0000, v26
	v_lshlrev_b32_e32 v118, 16, v27
	v_and_b32_e32 v119, 0xffff0000, v27
	v_pk_fma_f32 v[180:181], v[128:129], v[100:101], v[180:181]
	v_pk_fma_f32 v[230:231], v[130:131], v[118:119], v[230:231]
	v_pk_mul_f32 v[96:97], v[144:145], s[98:99]
	v_pk_mul_f32 v[98:99], v[178:179], s[98:99]
	v_pk_mul_f32 v[120:121], v[180:181], s[98:99]
	v_pk_mul_f32 v[122:123], v[230:231], s[98:99]
	v_exp_f32_e32 v96, v96
	v_exp_f32_e32 v97, v97
	v_exp_f32_e32 v98, v98
	v_exp_f32_e32 v99, v99
	v_exp_f32_e32 v120, v120
	v_exp_f32_e32 v121, v121
	v_exp_f32_e32 v122, v122
	v_exp_f32_e32 v123, v123
	v_pk_add_f32 v[96:97], v[96:97], s[100:101]
	v_pk_add_f32 v[98:99], v[98:99], s[100:101]
	v_pk_add_f32 v[120:121], v[120:121], s[100:101]
	v_pk_add_f32 v[122:123], v[122:123], s[100:101]
	v_rcp_f32_e32 v96, v96
	v_rcp_f32_e32 v97, v97
	v_rcp_f32_e32 v98, v98
	v_rcp_f32_e32 v99, v99
	v_rcp_f32_e32 v120, v120
	v_rcp_f32_e32 v121, v121
	v_rcp_f32_e32 v122, v122
	v_rcp_f32_e32 v123, v123
	v_pk_mul_f32 v[110:111], v[144:145], v[96:97]
	v_pk_mul_f32 v[112:113], v[178:179], v[98:99]
	v_pk_mul_f32 v[114:115], v[180:181], v[120:121]
	v_pk_mul_f32 v[116:117], v[230:231], v[122:123]
	v_cvt_pk_bf16_f32 v96, v104, v102
	v_cvt_pk_bf16_f32 v97, v105, v103
	v_add_u32_e32 v98, 0xd000, v206
	ds_write2_b32 v98, v96, v97 offset1:36
	v_cvt_pk_bf16_f32 v96, v106, v108
	v_cvt_pk_bf16_f32 v97, v107, v109
	ds_write2_b32 v98, v96, v97 offset0:72 offset1:108
	v_cvt_pk_bf16_f32 v96, v110, v114
	v_cvt_pk_bf16_f32 v97, v111, v115
	ds_write2_b32 v98, v96, v97 offset0:144 offset1:180
	v_cvt_pk_bf16_f32 v96, v112, v116
	v_cvt_pk_bf16_f32 v97, v113, v117
	ds_write2_b32 v98, v96, v97 offset0:216 offset1:252
	ds_read_b128 v[232:235], v187 offset:4608
	ds_read_b128 v[96:99], v187 offset:2560
	ds_read_b128 v[124:127], v187 offset:3072
	ds_read_b128 v[128:131], v187 offset:3584
	ds_read_b128 v[132:135], v187 offset:4096
	s_waitcnt vmcnt(2)
; __device__ __forceinline__ unsigned pk2(float lo, float hi) { unsigned r; asm("v_cvt_pk_bf16_f32 %0, %1, %2" : "=v"(r) : "v"(lo), "v"(hi)); return r; }
; __device__ __forceinline__ u32x4 pack8(const float (&o)[8]) { u32x4 r; r.x = pk2(o[0], o[1]); r.y = pk2(o[2], o[3]); r.z = pk2(o[4], o[5]); r.w = pk2(o[6], o[7]); return r; }
; __device__ __forceinline__ float silu_f(float v) { return v * __builtin_amdgcn_rcpf(1.f + __expf(-v)); }
; __device__ __forceinline__ void conv_rows(const u32x4 (&rawp)[5], const float* wl, float (&o0)[8], float (&o1)[8]) {
;     float raw[5][8];
; #pragma unroll
;     for (int q = 0; q < 5; ++q) unpack8(rawp[q], raw[q]);
; #pragma unroll
;     for (int h = 0; h < 2; ++h) {
;         const f32x4 bv = *(const f32x4*)(wl + 4 * 128 + h * 4);
;         f32x4 a0 = bv, a1 = bv;
; #pragma unroll
;         for (int k = 0; k < 4; ++k) { const f32x4 wv = *(const f32x4*)(wl + k * 128 + h * 4);
; #pragma unroll
;             for (int i = 0; i < 4; ++i) { a0[i] += wv[i] * raw[k][h * 4 + i]; a1[i] += wv[i] * raw[k + 1][h * 4 + i]; } }
; #pragma unroll
;         for (int i = 0; i < 4; ++i) { o0[h * 4 + i] = silu_f(a0[i]); o1[h * 4 + i] = silu_f(a1[i]); }
;         __builtin_amdgcn_sched_barrier(0);
;     }
; }
; __device__ __forceinline__ void phase_ssd(const Params& p, uchar* sm, int j, bf16_t* zx, const float* dtraw, float* ssqb) {
;     ...
;                 conv_rows(rb, wlb, t0, t1);
;                 __builtin_amdgcn_sched_barrier(0);
;                 *(u32x4*)(sm + L_B + (2 * lp) * RS_CB + c8 * 16) = pack8(t0);
;                 *(u32x4*)(sm + L_B + (2 * lp + 1) * RS_CB + c8 * 16) = pack8(t1);
; #pragma unroll
;                 for (int i = 0; i < 8; ++i) *(unsigned*)(sm + L_BT + (c8 * 8 + i) * RS_T + ((lp ^ swz) * 4)) = pk2(t0[i], t1[i]);
	v_lshlrev_b32_e32 v144, 16, v20
	v_and_b32_e32 v145, 0xffff0000, v20
	v_lshlrev_b32_e32 v178, 16, v21
	v_and_b32_e32 v179, 0xffff0000, v21
	s_waitcnt lgkmcnt(3)
	v_pk_fma_f32 v[180:181], v[96:97], v[144:145], v[232:233]
	v_pk_fma_f32 v[230:231], v[98:99], v[178:179], v[234:235]
	v_lshlrev_b32_e32 v144, 16, v28
	v_and_b32_e32 v145, 0xffff0000, v28
	v_lshlrev_b32_e32 v178, 16, v29
	v_and_b32_e32 v179, 0xffff0000, v29
	s_waitcnt lgkmcnt(2)
	v_pk_fma_f32 v[180:181], v[124:125], v[144:145], v[180:181]
	v_pk_fma_f32 v[230:231], v[126:127], v[178:179], v[230:231]
	v_pk_fma_f32 v[236:237], v[96:97], v[144:145], v[232:233]
	v_pk_fma_f32 v[238:239], v[98:99], v[178:179], v[234:235]
	v_lshlrev_b32_e32 v144, 16, v32
	v_and_b32_e32 v145, 0xffff0000, v32
	v_lshlrev_b32_e32 v178, 16, v33
	v_and_b32_e32 v179, 0xffff0000, v33
	s_waitcnt lgkmcnt(1)
	v_pk_fma_f32 v[180:181], v[128:129], v[144:145], v[180:181]
	v_pk_fma_f32 v[230:231], v[130:131], v[178:179], v[230:231]
	v_pk_fma_f32 v[236:237], v[124:125], v[144:145], v[236:237]
	v_pk_fma_f32 v[238:239], v[126:127], v[178:179], v[238:239]
	v_lshlrev_b32_e32 v144, 16, v36
	v_and_b32_e32 v145, 0xffff0000, v36
	v_lshlrev_b32_e32 v178, 16, v37
	v_and_b32_e32 v179, 0xffff0000, v37
	s_waitcnt lgkmcnt(0)
	v_pk_fma_f32 v[180:181], v[132:133], v[144:145], v[180:181]
	v_pk_fma_f32 v[230:231], v[134:135], v[178:179], v[230:231]
	v_pk_fma_f32 v[236:237], v[128:129], v[144:145], v[236:237]
	v_pk_fma_f32 v[238:239], v[130:131], v[178:179], v[238:239]
	v_lshlrev_b32_e32 v144, 16, v40
	v_and_b32_e32 v145, 0xffff0000, v40
	v_lshlrev_b32_e32 v178, 16, v41
	v_and_b32_e32 v179, 0xffff0000, v41
	v_pk_fma_f32 v[236:237], v[132:133], v[144:145], v[236:237]
	v_pk_fma_f32 v[238:239], v[134:135], v[178:179], v[238:239]
	v_pk_mul_f32 v[96:97], v[180:181], s[98:99]
	v_pk_mul_f32 v[98:99], v[230:231], s[98:99]
	v_pk_mul_f32 v[124:125], v[236:237], s[98:99]
	v_pk_mul_f32 v[126:127], v[238:239], s[98:99]
	v_exp_f32_e32 v96, v96
	v_exp_f32_e32 v97, v97
	v_exp_f32_e32 v98, v98
	v_exp_f32_e32 v99, v99
	v_exp_f32_e32 v124, v124
	v_exp_f32_e32 v125, v125
	v_exp_f32_e32 v126, v126
	v_exp_f32_e32 v127, v127
	v_pk_add_f32 v[96:97], v[96:97], s[100:101]
	v_pk_add_f32 v[98:99], v[98:99], s[100:101]
	v_pk_add_f32 v[124:125], v[124:125], s[100:101]
	v_pk_add_f32 v[126:127], v[126:127], s[100:101]
	ds_read_b128 v[232:235], v187 offset:4624
	ds_read_b128 v[120:123], v187 offset:2576
	v_rcp_f32_e32 v96, v96
	v_rcp_f32_e32 v97, v97
	v_rcp_f32_e32 v98, v98
	ds_read_b128 v[248:251], v187 offset:3088
	v_rcp_f32_e32 v99, v99
	v_rcp_f32_e32 v124, v124
	v_rcp_f32_e32 v125, v125
	v_rcp_f32_e32 v126, v126
	ds_read_b128 v[128:131], v187 offset:3600
	v_rcp_f32_e32 v127, v127
	v_pk_mul_f32 v[240:241], v[180:181], v[96:97]
	v_pk_mul_f32 v[246:247], v[230:231], v[98:99]
	v_pk_mul_f32 v[242:243], v[236:237], v[124:125]
	ds_read_b128 v[132:135], v187 offset:4112
	v_pk_mul_f32 v[252:253], v[238:239], v[126:127]
	v_lshlrev_b32_e32 v144, 16, v22
	v_and_b32_e32 v145, 0xffff0000, v22
	v_lshlrev_b32_e32 v178, 16, v23
	v_and_b32_e32 v179, 0xffff0000, v23
	s_waitcnt lgkmcnt(3)
	v_pk_fma_f32 v[180:181], v[120:121], v[144:145], v[232:233]
	v_pk_fma_f32 v[230:231], v[122:123], v[178:179], v[234:235]
	v_lshlrev_b32_e32 v144, 16, v30
	v_and_b32_e32 v145, 0xffff0000, v30
	v_lshlrev_b32_e32 v178, 16, v31
	v_and_b32_e32 v179, 0xffff0000, v31
	s_waitcnt lgkmcnt(2)
	v_pk_fma_f32 v[180:181], v[248:249], v[144:145], v[180:181]
	v_pk_fma_f32 v[230:231], v[250:251], v[178:179], v[230:231]
	v_pk_fma_f32 v[236:237], v[120:121], v[144:145], v[232:233]
	v_pk_fma_f32 v[238:239], v[122:123], v[178:179], v[234:235]
	v_lshlrev_b32_e32 v144, 16, v34
	v_and_b32_e32 v145, 0xffff0000, v34
	v_lshlrev_b32_e32 v178, 16, v35
	v_and_b32_e32 v179, 0xffff0000, v35
	s_waitcnt lgkmcnt(1)
	v_pk_fma_f32 v[180:181], v[128:129], v[144:145], v[180:181]
	v_pk_fma_f32 v[230:231], v[130:131], v[178:179], v[230:231]
	v_pk_fma_f32 v[236:237], v[248:249], v[144:145], v[236:237]
	v_pk_fma_f32 v[238:239], v[250:251], v[178:179], v[238:239]
	v_lshlrev_b32_e32 v144, 16, v38
	v_and_b32_e32 v145, 0xffff0000, v38
	v_lshlrev_b32_e32 v178, 16, v39
	v_and_b32_e32 v179, 0xffff0000, v39
	s_waitcnt lgkmcnt(0)
	v_pk_fma_f32 v[180:181], v[132:133], v[144:145], v[180:181]
	v_pk_fma_f32 v[230:231], v[134:135], v[178:179], v[230:231]
	v_pk_fma_f32 v[236:237], v[128:129], v[144:145], v[236:237]
	v_pk_fma_f32 v[238:239], v[130:131], v[178:179], v[238:239]
	v_lshlrev_b32_e32 v144, 16, v42
	v_and_b32_e32 v145, 0xffff0000, v42
	v_lshlrev_b32_e32 v178, 16, v43
	v_and_b32_e32 v179, 0xffff0000, v43
	v_pk_fma_f32 v[236:237], v[132:133], v[144:145], v[236:237]
	v_pk_fma_f32 v[238:239], v[134:135], v[178:179], v[238:239]
	v_pk_mul_f32 v[96:97], v[180:181], s[98:99]
	v_pk_mul_f32 v[98:99], v[230:231], s[98:99]
	v_pk_mul_f32 v[124:125], v[236:237], s[98:99]
	v_pk_mul_f32 v[126:127], v[238:239], s[98:99]
	v_exp_f32_e32 v96, v96
	v_exp_f32_e32 v97, v97
	v_exp_f32_e32 v98, v98
	v_exp_f32_e32 v99, v99
	v_exp_f32_e32 v124, v124
	v_exp_f32_e32 v125, v125
	v_exp_f32_e32 v126, v126
	v_exp_f32_e32 v127, v127
	v_pk_add_f32 v[96:97], v[96:97], s[100:101]
	v_pk_add_f32 v[98:99], v[98:99], s[100:101]
	v_pk_add_f32 v[124:125], v[124:125], s[100:101]
	v_pk_add_f32 v[126:127], v[126:127], s[100:101]
	v_rcp_f32_e32 v96, v96
	v_rcp_f32_e32 v97, v97
	v_rcp_f32_e32 v98, v98
	v_rcp_f32_e32 v99, v99
	v_rcp_f32_e32 v124, v124
	v_rcp_f32_e32 v125, v125
	v_rcp_f32_e32 v126, v126
	v_rcp_f32_e32 v127, v127
	v_pk_mul_f32 v[120:121], v[180:181], v[96:97]
	v_pk_mul_f32 v[118:119], v[230:231], v[98:99]
	v_pk_mul_f32 v[122:123], v[236:237], v[124:125]
	v_pk_mul_f32 v[100:101], v[238:239], v[126:127]
	v_cvt_pk_bf16_f32 v96, v240, v241
	v_cvt_pk_bf16_f32 v97, v246, v247
	v_cvt_pk_bf16_f32 v98, v120, v121
	v_cvt_pk_bf16_f32 v99, v118, v119
	ds_write_b128 v207, v[96:99] offset:17408
	v_cvt_pk_bf16_f32 v96, v242, v243
	v_cvt_pk_bf16_f32 v97, v252, v253
	v_cvt_pk_bf16_f32 v98, v122, v123
	v_cvt_pk_bf16_f32 v99, v100, v101
	ds_write_b128 v208, v[96:99] offset:17408
	v_cvt_pk_bf16_f32 v96, v240, v242
	v_cvt_pk_bf16_f32 v97, v241, v243
	v_add_u32_e32 v98, 0x8800, v206
	ds_write2_b32 v98, v96, v97 offset1:36
	v_cvt_pk_bf16_f32 v96, v246, v252
	v_cvt_pk_bf16_f32 v97, v247, v253
	ds_write2_b32 v98, v96, v97 offset0:72 offset1:108
	v_cvt_pk_bf16_f32 v96, v120, v122
	v_cvt_pk_bf16_f32 v97, v121, v123
	ds_write2_b32 v98, v96, v97 offset0:144 offset1:180
	v_cvt_pk_bf16_f32 v96, v118, v100
	v_cvt_pk_bf16_f32 v97, v119, v101
	ds_write2_b32 v98, v96, v97 offset0:216 offset1:252
	ds_read_b128 v[236:239], v187 offset:7168
	ds_read_b128 v[124:127], v187 offset:5120
	ds_read_b128 v[128:131], v187 offset:5632
	ds_read_b128 v[132:135], v187 offset:6144
	ds_read_b128 v[232:235], v187 offset:6656
	v_lshlrev_b32_e32 v96, 16, v44
	v_and_b32_e32 v97, 0xffff0000, v44
	v_lshlrev_b32_e32 v144, 16, v45
	v_and_b32_e32 v145, 0xffff0000, v45
	s_waitcnt lgkmcnt(3)
; __device__ __forceinline__ u32x4 pack8(const float (&o)[8]) { u32x4 r; r.x = pk2(o[0], o[1]); r.y = pk2(o[2], o[3]); r.z = pk2(o[4], o[5]); r.w = pk2(o[6], o[7]); return r; }
; __device__ __forceinline__ float silu_f(float v) { return v * __builtin_amdgcn_rcpf(1.f + __expf(-v)); }
; __device__ __forceinline__ void conv_rows(const u32x4 (&rawp)[5], const float* wl, float (&o0)[8], float (&o1)[8]) {
;     float raw[5][8];
; #pragma unroll
;     for (int q = 0; q < 5; ++q) unpack8(rawp[q], raw[q]);
; #pragma unroll
;     for (int h = 0; h < 2; ++h) {
;         const f32x4 bv = *(const f32x4*)(wl + 4 * 128 + h * 4);
;         f32x4 a0 = bv, a1 = bv;
; #pragma unroll
;         for (int k = 0; k < 4; ++k) { const f32x4 wv = *(const f32x4*)(wl + k * 128 + h * 4);
; #pragma unroll
;             for (int i = 0; i < 4; ++i) { a0[i] += wv[i] * raw[k][h * 4 + i]; a1[i] += wv[i] * raw[k + 1][h * 4 + i]; } }
; #pragma unroll
;         for (int i = 0; i < 4; ++i) { o0[h * 4 + i] = silu_f(a0[i]); o1[h * 4 + i] = silu_f(a1[i]); }
;         __builtin_amdgcn_sched_barrier(0);
;     }
; }
; __device__ __forceinline__ void phase_ssd(const Params& p, uchar* sm, int j, bf16_t* zx, const float* dtraw, float* ssqb) {
;     ...
;                 conv_rows(rc, wlc, t0, t1);
;                 __builtin_amdgcn_sched_barrier(0);
;                 *(u32x4*)(sm + L_C + (2 * lp) * RS_CB + c8 * 16) = pack8(t0);
;                 *(u32x4*)(sm + L_C + (2 * lp + 1) * RS_CB + c8 * 16) = pack8(t1);
;             }
;             const u32x4 xp0 = pack8(xo0), xp1 = pack8(xo1);
;             bf16_t* zc = zx + (size_t)zrow0 * LDZ;
;             if (c + 1 < 32) { const bf16_t* zb = zc + 64 * LDZ;
;                 load_raw(zb + 2048 + colx, toff, false, 2 * lp, rx); }
;             const u32x4 z0 = *(const u32x4*)(zc + colx + toff), z1 = *(const u32x4*)(zc + colx + LDZ + toff);
	v_pk_fma_f32 v[178:179], v[124:125], v[96:97], v[236:237]
	v_pk_fma_f32 v[180:181], v[126:127], v[144:145], v[238:239]
	v_lshlrev_b32_e32 v96, 16, v48
	v_and_b32_e32 v97, 0xffff0000, v48
	v_lshlrev_b32_e32 v144, 16, v49
	v_and_b32_e32 v145, 0xffff0000, v49
	s_waitcnt lgkmcnt(2)
	v_pk_fma_f32 v[178:179], v[128:129], v[96:97], v[178:179]
	v_pk_fma_f32 v[180:181], v[130:131], v[144:145], v[180:181]
	v_pk_fma_f32 v[230:231], v[124:125], v[96:97], v[236:237]
	v_pk_fma_f32 v[246:247], v[126:127], v[144:145], v[238:239]
	v_lshlrev_b32_e32 v96, 16, v52
	v_and_b32_e32 v97, 0xffff0000, v52
	v_lshlrev_b32_e32 v144, 16, v53
	v_and_b32_e32 v145, 0xffff0000, v53
	s_waitcnt lgkmcnt(1)
	v_pk_fma_f32 v[178:179], v[132:133], v[96:97], v[178:179]
	v_pk_fma_f32 v[180:181], v[134:135], v[144:145], v[180:181]
	v_pk_fma_f32 v[230:231], v[128:129], v[96:97], v[230:231]
	v_pk_fma_f32 v[246:247], v[130:131], v[144:145], v[246:247]
	v_lshlrev_b32_e32 v96, 16, v56
	v_and_b32_e32 v97, 0xffff0000, v56
	v_lshlrev_b32_e32 v144, 16, v57
	v_and_b32_e32 v145, 0xffff0000, v57
	s_waitcnt lgkmcnt(0)
	v_pk_fma_f32 v[178:179], v[232:233], v[96:97], v[178:179]
	v_pk_fma_f32 v[180:181], v[234:235], v[144:145], v[180:181]
	v_pk_fma_f32 v[230:231], v[132:133], v[96:97], v[230:231]
	v_pk_fma_f32 v[246:247], v[134:135], v[144:145], v[246:247]
	v_lshlrev_b32_e32 v96, 16, v60
	v_and_b32_e32 v97, 0xffff0000, v60
	v_lshlrev_b32_e32 v144, 16, v61
	v_and_b32_e32 v145, 0xffff0000, v61
	v_pk_fma_f32 v[230:231], v[232:233], v[96:97], v[230:231]
	v_pk_fma_f32 v[246:247], v[234:235], v[144:145], v[246:247]
	v_pk_mul_f32 v[124:125], v[178:179], s[98:99]
	v_pk_mul_f32 v[126:127], v[180:181], s[98:99]
	v_pk_mul_f32 v[128:129], v[230:231], s[98:99]
	v_pk_mul_f32 v[130:131], v[246:247], s[98:99]
	v_exp_f32_e32 v124, v124
	v_exp_f32_e32 v125, v125
	v_exp_f32_e32 v126, v126
	v_exp_f32_e32 v127, v127
	v_exp_f32_e32 v128, v128
	v_exp_f32_e32 v129, v129
	v_exp_f32_e32 v130, v130
	v_exp_f32_e32 v131, v131
	v_pk_add_f32 v[124:125], v[124:125], s[100:101]
	v_pk_add_f32 v[126:127], v[126:127], s[100:101]
	v_pk_add_f32 v[128:129], v[128:129], s[100:101]
	v_pk_add_f32 v[130:131], v[130:131], s[100:101]
	ds_read_b128 v[236:239], v187 offset:7184
	ds_read_b128 v[120:123], v187 offset:5136
	v_rcp_f32_e32 v124, v124
	v_rcp_f32_e32 v125, v125
	v_rcp_f32_e32 v126, v126
	ds_read_b128 v[248:251], v187 offset:5648
	v_rcp_f32_e32 v127, v127
	v_rcp_f32_e32 v128, v128
	v_rcp_f32_e32 v129, v129
	v_rcp_f32_e32 v130, v130
	ds_read_b128 v[132:135], v187 offset:6160
	v_rcp_f32_e32 v131, v131
	v_mul_f32_e32 v139, v178, v124
	v_mul_f32_e32 v170, v179, v125
	v_pk_mul_f32 v[240:241], v[180:181], v[126:127]
	v_pk_mul_f32 v[242:243], v[230:231], v[128:129]
	ds_read_b128 v[232:235], v187 offset:6672
	v_pk_mul_f32 v[252:253], v[246:247], v[130:131]
	v_lshlrev_b32_e32 v96, 16, v46
	v_and_b32_e32 v97, 0xffff0000, v46
	v_lshlrev_b32_e32 v144, 16, v47
	v_and_b32_e32 v145, 0xffff0000, v47
	s_waitcnt lgkmcnt(3)
	v_pk_fma_f32 v[178:179], v[120:121], v[96:97], v[236:237]
	v_pk_fma_f32 v[180:181], v[122:123], v[144:145], v[238:239]
	v_lshlrev_b32_e32 v96, 16, v50
	v_and_b32_e32 v97, 0xffff0000, v50
	v_lshlrev_b32_e32 v144, 16, v51
	v_and_b32_e32 v145, 0xffff0000, v51
	s_waitcnt lgkmcnt(2)
	v_pk_fma_f32 v[178:179], v[248:249], v[96:97], v[178:179]
	v_pk_fma_f32 v[180:181], v[250:251], v[144:145], v[180:181]
	v_pk_fma_f32 v[230:231], v[120:121], v[96:97], v[236:237]
	v_pk_fma_f32 v[246:247], v[122:123], v[144:145], v[238:239]
	v_lshlrev_b32_e32 v96, 16, v54
	v_and_b32_e32 v97, 0xffff0000, v54
	v_lshlrev_b32_e32 v144, 16, v55
	v_and_b32_e32 v145, 0xffff0000, v55
	s_waitcnt lgkmcnt(1)
	v_pk_fma_f32 v[178:179], v[132:133], v[96:97], v[178:179]
	v_pk_fma_f32 v[180:181], v[134:135], v[144:145], v[180:181]
	v_pk_fma_f32 v[230:231], v[248:249], v[96:97], v[230:231]
	v_pk_fma_f32 v[246:247], v[250:251], v[144:145], v[246:247]
	v_lshlrev_b32_e32 v96, 16, v58
	v_and_b32_e32 v97, 0xffff0000, v58
	v_lshlrev_b32_e32 v144, 16, v59
	v_and_b32_e32 v145, 0xffff0000, v59
	s_waitcnt lgkmcnt(0)
	v_pk_fma_f32 v[178:179], v[232:233], v[96:97], v[178:179]
	v_pk_fma_f32 v[180:181], v[234:235], v[144:145], v[180:181]
	v_pk_fma_f32 v[230:231], v[132:133], v[96:97], v[230:231]
	v_pk_fma_f32 v[246:247], v[134:135], v[144:145], v[246:247]
	v_lshlrev_b32_e32 v96, 16, v62
	v_and_b32_e32 v97, 0xffff0000, v62
	v_lshlrev_b32_e32 v144, 16, v63
	v_and_b32_e32 v145, 0xffff0000, v63
	v_pk_fma_f32 v[230:231], v[232:233], v[96:97], v[230:231]
	v_pk_fma_f32 v[246:247], v[234:235], v[144:145], v[246:247]
	v_pk_mul_f32 v[124:125], v[178:179], s[98:99]
	v_pk_mul_f32 v[126:127], v[180:181], s[98:99]
	v_pk_mul_f32 v[128:129], v[230:231], s[98:99]
	v_pk_mul_f32 v[130:131], v[246:247], s[98:99]
	v_exp_f32_e32 v124, v124
	v_exp_f32_e32 v125, v125
	v_exp_f32_e32 v126, v126
	v_exp_f32_e32 v127, v127
	v_exp_f32_e32 v128, v128
	v_exp_f32_e32 v129, v129
	v_exp_f32_e32 v130, v130
	v_exp_f32_e32 v131, v131
	v_pk_add_f32 v[124:125], v[124:125], s[100:101]
	v_pk_add_f32 v[126:127], v[126:127], s[100:101]
	v_pk_add_f32 v[128:129], v[128:129], s[100:101]
	v_pk_add_f32 v[130:131], v[130:131], s[100:101]
	v_rcp_f32_e32 v124, v124
	v_rcp_f32_e32 v125, v125
	v_rcp_f32_e32 v126, v126
	v_rcp_f32_e32 v127, v127
	v_rcp_f32_e32 v128, v128
	v_rcp_f32_e32 v129, v129
	v_rcp_f32_e32 v130, v130
	v_rcp_f32_e32 v131, v131
	v_mul_f32_e32 v122, v178, v124
	v_mul_f32_e32 v99, v179, v125
	v_pk_mul_f32 v[100:101], v[180:181], v[126:127]
	v_pk_mul_f32 v[118:119], v[230:231], v[128:129]
	v_pk_mul_f32 v[120:121], v[246:247], v[130:131]
	v_readlane_b32 s60, v254, 0
	s_cmp_lg_u32 s83, 1
	v_readlane_b32 s66, v254, 6
	v_readlane_b32 s67, v254, 7
	v_cvt_pk_bf16_f32 v96, v139, v170
	v_cvt_pk_bf16_f32 v97, v240, v241
	v_cvt_pk_bf16_f32 v98, v122, v99
	v_cvt_pk_bf16_f32 v99, v100, v101
	v_cvt_pk_bf16_f32 v235, v104, v105
	v_cvt_pk_bf16_f32 v231, v102, v103
	s_cselect_b64 s[0:1], -1, 0
	s_cmp_eq_u32 s83, 1
	v_lshl_add_u64 v[104:105], s[66:67], 0, v[174:175]
	ds_write_b128 v207, v[96:99]
	v_cvt_pk_bf16_f32 v96, v242, v243
	v_cvt_pk_bf16_f32 v97, v252, v253
	v_cvt_pk_bf16_f32 v98, v118, v119
	v_cvt_pk_bf16_f32 v99, v120, v121
	ds_write_b128 v208, v[96:99]
	v_cvt_pk_bf16_f32 v233, v106, v107
	v_cvt_pk_bf16_f32 v236, v110, v111
	v_cvt_pk_bf16_f32 v234, v112, v113
	v_cvt_pk_bf16_f32 v229, v108, v109
	v_cvt_pk_bf16_f32 v232, v114, v115
	v_cvt_pk_bf16_f32 v230, v116, v117
	v_readlane_b32 s61, v254, 1
	v_readlane_b32 s62, v254, 2
	v_readlane_b32 s63, v254, 3
	v_readlane_b32 s64, v254, 4
	v_readlane_b32 s65, v254, 5
	s_cbranch_scc1 .LBB0_468
; __device__ __forceinline__ void load_raw(const bf16_t* base, int toff, bool first, int lrow, u32x4 (&raw)[5]) {
; #pragma unroll
;     for (int q = 0; q < 5; ++q) {
;         if (!first || lrow - 3 + q >= 0) raw[q] = *(const u32x4*)(base + (q - 3) * LDZ + toff);
;         else raw[q] = (u32x4){0u, 0u, 0u, 0u}; }
; __device__ __forceinline__ void phase_ssd(const Params& p, uchar* sm, int j, bf16_t* zx, const float* dtraw, float* ssqb) {
;     ...
;             if (c + 1 < 32) { const bf16_t* zb = zc + 64 * LDZ;
;                 load_raw(zb + 2048 + colx, toff, false, 2 * lp, rx); }
;             const u32x4 z0 = *(const u32x4*)(zc + colx + toff), z1 = *(const u32x4*)(zc + colx + LDZ + toff);
;             __syncthreads();
;             if (tabw) {
;                 const float v = dtr + dtb;
;                 const float dt = v > 20.f ? v : log1pf(__expf(v));
;                 const float cs = wave_incl_scan(dt * a_coef);
;                 const float c63 = __int_as_float(__builtin_amdgcn_readlane(__float_as_int(cs), 63));
;                 dtL[th * 64 + lane] = dt; csL[th * 64 + lane] = cs; e1L[th * 64 + lane] = __expf(cs); e2L[th * 64 + lane] = dt * __expf(c63 - cs);
;                 if (c + 1 < 32) dtr = dtraw[(zrow0 + 64 + lane) * 32 + headA + th];
;             } else {
;                 const int lt = w >> 1, st0 = (w & 1) * 2;
;                 f32x4 cacc[2] = {(f32x4){0.f, 0.f, 0.f, 0.f}, (f32x4){0.f, 0.f, 0.f, 0.f}};
; #pragma unroll
;                 for (int ks = 0; ks < 4; ++ks) {
;                     const bf16x8 a = *(const bf16x8*)(sm + L_C + (lt * 16 + l15) * RS_CB + (ks * 32 + quad * 8) * 2);
; #pragma unroll
;                     for (int q = 0; q < 2; ++q) { const bf16x8 b = *(const bf16x8*)(sm + L_B + ((st0 + q) * 16 + l15) * RS_CB + (ks * 32 + quad * 8) * 2);
;                         cacc[q] = __builtin_amdgcn_mfma_f32_16x16x32_bf16(a, b, cacc[q], 0, 0, 0); }
;                 }
; #pragma unroll
;                 for (int q = 0; q < 2; ++q)
; #pragma unroll
;                     for (int r = 0; r < 4; ++r) *(float*)(sm + L_CB + (lt * 16 + quad * 4 + r) * RS_CB + ((st0 + q) * 16 + l15) * 4) = cacc[q][r];
	s_mov_b64 vcc, 0x64d5000
	v_lshl_add_u64 v[4:5], v[104:105], 0, vcc
	s_mov_b64 vcc, 0x64d8000
	v_lshl_add_u64 v[8:9], v[104:105], 0, vcc
	s_mov_b64 vcc, 0x64db000
	v_lshl_add_u64 v[12:13], v[104:105], 0, vcc
	global_load_dwordx4 v[4:7], v[4:5], off offset:3712
	s_nop 0
	global_load_dwordx4 v[8:11], v[8:9], off offset:3840
	s_mov_b64 vcc, 0x64df000
	v_lshl_add_u64 v[16:17], v[104:105], 0, vcc
	s_mov_b64 vcc, 0x64e2000
	v_lshl_add_u64 v[24:25], v[104:105], 0, vcc
	global_load_dwordx4 v[12:15], v[12:13], off offset:3968
	s_nop 0
	global_load_dwordx4 v[16:19], v[16:17], off
	global_load_dwordx4 v[24:27], v[24:25], off offset:128
.LBB0_468:
	s_mov_b64 vcc, 0x641c000
	v_lshl_add_u64 v[96:97], v[104:105], 0, vcc
	s_mov_b64 vcc, 0x641f000
	v_lshl_add_u64 v[98:99], v[104:105], 0, vcc
	global_load_dwordx4 v[100:103], v[96:97], off
	s_nop 0
	global_load_dwordx4 v[96:99], v[98:99], off offset:128
	s_waitcnt lgkmcnt(0)
	s_barrier
	s_and_saveexec_b64 s[4:5], s[8:9]
	s_xor_b64 s[4:5], exec, s[4:5]
	s_cbranch_execz .LBB0_470
	ds_read_b128 v[106:109], v209
	ds_read_b128 v[110:113], v210 offset:17408
	ds_read_b128 v[114:117], v211 offset:17408
	ds_read_b128 v[122:125], v209 offset:64
	ds_read_b128 v[118:121], v210 offset:17472
	ds_read_b128 v[126:129], v211 offset:17472
	ds_read_b128 v[130:133], v209 offset:128
	ds_read_b128 v[178:181], v210 offset:17536
	ds_read_b128 v[238:241], v211 offset:17536
	s_waitcnt lgkmcnt(6)
	v_mfma_f32_16x16x32_bf16 v[110:113], v[106:109], v[110:113], 0
	v_mfma_f32_16x16x32_bf16 v[106:109], v[106:109], v[114:117], 0
	ds_read_b128 v[114:117], v209 offset:192
	ds_read_b128 v[242:245], v210 offset:17600
	s_waitcnt lgkmcnt(6)
	v_mfma_f32_16x16x32_bf16 v[110:113], v[122:125], v[118:121], v[110:113]
	ds_read_b128 v[118:121], v211 offset:17600
	s_waitcnt lgkmcnt(3)
	v_mfma_f32_16x16x32_bf16 v[106:109], v[122:125], v[126:129], v[106:109]
	v_mfma_f32_16x16x32_bf16 v[110:113], v[130:133], v[178:181], v[110:113]
	v_mfma_f32_16x16x32_bf16 v[106:109], v[130:133], v[238:241], v[106:109]
	s_waitcnt lgkmcnt(0)
	v_mfma_f32_16x16x32_bf16 v[110:113], v[114:117], v[242:245], v[110:113]
	v_mfma_f32_16x16x32_bf16 v[106:109], v[114:117], v[118:121], v[106:109]
	s_nop 4
	s_nop 1
	ds_write2_b32 v212, v110, v111 offset1:68
	ds_write2_b32 v212, v112, v113 offset0:136 offset1:204
	s_nop 0
	ds_write2_b32 v213, v106, v107 offset1:68
	ds_write2_b32 v213, v108, v109 offset0:136 offset1:204

; __device__ __forceinline__ unsigned pk2(float lo, float hi) { unsigned r; asm("v_cvt_pk_bf16_f32 %0, %1, %2" : "=v"(r) : "v"(lo), "v"(hi)); return r; }
; __device__ __forceinline__ void phase_ssd(const Params& p, uchar* sm, int j, bf16_t* zx, const float* dtraw, float* ssqb) {
;     ...
;                 uchar* stw = sm + L_ST + w * (16 * RS_CB);
; #pragma unroll
;                 for (int n = 0; n < 8; ++n) { u32x2 o; o.x = pk2(st[n][0], st[n][1]); o.y = pk2(st[n][2], st[n][3]);
;                     *(u32x2*)(stw + l15 * RS_CB + (n * 16 + quad * 4) * 2) = o; }
; #pragma unroll
;                 for (int m = 0; m < 4; ++m) yacc[m] = (f32x4){0.f, 0.f, 0.f, 0.f};
; #pragma unroll
;                 for (int ks = 0; ks < 4; ++ks) {
;                     const bf16x8 bfr = *(const bf16x8*)(stw + l15 * RS_CB + (ks * 32 + quad * 8) * 2);
; #pragma unroll
;                     for (int m = 0; m < 4; ++m) { const bf16x8 afr = *(const bf16x8*)(sm + L_C + (m * 16 + l15) * RS_CB + (ks * 32 + quad * 8) * 2);
;                         yacc[m] = __builtin_amdgcn_mfma_f32_16x16x32_bf16(afr, bfr, yacc[m], 0, 0, 0); }
;                 }
; #pragma unroll
;                 for (int m = 0; m < 4; ++m) { const f32x4 ev = *(const f32x4*)(e1L + rl * 64 + m * 16 + quad * 4);
; #pragma unroll
;                     for (int r = 0; r < 4; ++r) yacc[m][r] *= ev[r]; }
;                 const float cs63 = csL[rl * 64 + 63];
;                 bf16x8 xdt[2], xdd[2];
; #pragma unroll
;                 for (int ks = 0; ks < 2; ++ks) {
;                     float xr[8]; unpack8(*(const u32x4*)(sm + L_XT + (chl + l15) * RS_T + (((ks * 16 + quad * 4) ^ (4 * w)) * 4)), xr);
;                     const f32x4 d0 = *(const f32x4*)(dtL + rl * 64 + ks * 32 + quad * 8), d1 = *(const f32x4*)(dtL + rl * 64 + ks * 32 + quad * 8 + 4);
;                     const f32x4 g0 = *(const f32x4*)(e2L + rl * 64 + ks * 32 + quad * 8), g1 = *(const f32x4*)(e2L + rl * 64 + ks * 32 + quad * 8 + 4);
;                     float a[8], b[8];
; #pragma unroll
;                     for (int i = 0; i < 4; ++i) { a[i] = xr[i] * d0[i]; a[4 + i] = xr[4 + i] * d1[i]; b[i] = xr[i] * g0[i]; b[4 + i] = xr[4 + i] * g1[i]; }
;                     const u32x4 pa = pack8(a), pb = pack8(b);
;                     xdt[ks] = __builtin_bit_cast(bf16x8, pa); xdd[ks] = __builtin_bit_cast(bf16x8, pb);
;                 }
.LBB0_477:
	s_or_b64 exec, exec, s[4:5]
	v_cvt_pk_bf16_f32 v104, v72, v73
	v_cvt_pk_bf16_f32 v105, v74, v75
	v_add_u32_e32 v108, v200, v194
	v_cvt_pk_bf16_f32 v106, v76, v77
	v_cvt_pk_bf16_f32 v107, v78, v79
	ds_write2_b64 v108, v[104:105], v[106:107] offset1:4
	v_cvt_pk_bf16_f32 v104, v64, v65
	v_cvt_pk_bf16_f32 v105, v66, v67
	v_cvt_pk_bf16_f32 v106, v68, v69
	v_cvt_pk_bf16_f32 v107, v70, v71
	ds_write2_b64 v108, v[104:105], v[106:107] offset0:8 offset1:12
	v_cvt_pk_bf16_f32 v104, v92, v93
	v_cvt_pk_bf16_f32 v105, v94, v95
	v_cvt_pk_bf16_f32 v106, v80, v81
	v_cvt_pk_bf16_f32 v107, v82, v83
	ds_write2_b64 v108, v[104:105], v[106:107] offset0:16 offset1:20
	v_cvt_pk_bf16_f32 v104, v84, v85
	v_cvt_pk_bf16_f32 v105, v86, v87
	v_cvt_pk_bf16_f32 v106, v88, v89
	v_cvt_pk_bf16_f32 v107, v90, v91
	ds_write2_b64 v108, v[104:105], v[106:107] offset0:24 offset1:28
	v_add_u32_e32 v128, v200, v188
	ds_read_b128 v[104:107], v128
	v_add_u32_e32 v129, v204, v199
	ds_read_b128 v[108:111], v129
	ds_read_b128 v[112:115], v216
	ds_read_b128 v[116:119], v216 offset:4352
	ds_read_b128 v[120:123], v216 offset:8704
	ds_read_b128 v[132:135], v128 offset:64
	ds_read_b128 v[124:127], v129 offset:64
	ds_read_b128 v[240:243], v216 offset:64
	ds_read_b128 v[244:247], v216 offset:4416
	ds_read_b128 v[248:251], v216 offset:8768
	s_waitcnt lgkmcnt(7)
	v_mfma_f32_16x16x32_bf16 v[108:111], v[108:111], v[104:107], 0
	s_andn2_b64 vcc, exec, s[0:1]
	v_mfma_f32_16x16x32_bf16 v[112:115], v[112:115], v[104:107], 0
	s_waitcnt lgkmcnt(5)
	v_mfma_f32_16x16x32_bf16 v[116:119], v[116:119], v[104:107], 0
	v_mfma_f32_16x16x32_bf16 v[104:107], v[120:123], v[104:107], 0
	ds_read_b128 v[120:123], v128 offset:128
	s_waitcnt lgkmcnt(4)
	v_mfma_f32_16x16x32_bf16 v[108:111], v[124:127], v[132:135], v[108:111]
	ds_read_b128 v[124:127], v129 offset:128
	s_waitcnt lgkmcnt(4)
	v_mfma_f32_16x16x32_bf16 v[112:115], v[240:243], v[132:135], v[112:115]
	ds_read_b128 v[240:243], v216 offset:128
	s_waitcnt lgkmcnt(4)
	v_mfma_f32_16x16x32_bf16 v[116:119], v[244:247], v[132:135], v[116:119]
	ds_read_b128 v[244:247], v216 offset:4480
	s_waitcnt lgkmcnt(4)
	v_mfma_f32_16x16x32_bf16 v[104:107], v[248:251], v[132:135], v[104:107]
	ds_read_b128 v[132:135], v216 offset:8832
	ds_read_b128 v[248:251], v128 offset:192
	s_waitcnt lgkmcnt(4)
	v_mfma_f32_16x16x32_bf16 v[108:111], v[124:127], v[120:123], v[108:111]
	ds_read_b128 v[124:127], v129 offset:192
	s_waitcnt lgkmcnt(4)
	v_mfma_f32_16x16x32_bf16 v[112:115], v[240:243], v[120:123], v[112:115]
	ds_read_b128 v[240:243], v216 offset:192
	s_waitcnt lgkmcnt(4)
	v_mfma_f32_16x16x32_bf16 v[116:119], v[244:247], v[120:123], v[116:119]
	ds_read_b128 v[244:247], v216 offset:4544
	s_waitcnt lgkmcnt(4)
	v_mfma_f32_16x16x32_bf16 v[104:107], v[132:135], v[120:123], v[104:107]
	ds_read_b128 v[128:131], v216 offset:8896
	ds_read_b128 v[120:123], v217
	ds_read_b128 v[132:135], v217 offset:64
	s_waitcnt lgkmcnt(5)
	v_mfma_f32_16x16x32_bf16 v[108:111], v[124:127], v[248:251], v[108:111]
	ds_read_b128 v[124:127], v217 offset:128
	s_waitcnt lgkmcnt(5)
	v_mfma_f32_16x16x32_bf16 v[112:115], v[240:243], v[248:251], v[112:115]
	ds_read_b128 v[240:243], v217 offset:192
	s_waitcnt lgkmcnt(4)
	v_mfma_f32_16x16x32_bf16 v[116:119], v[244:247], v[248:251], v[116:119]
	v_mfma_f32_16x16x32_bf16 v[104:107], v[128:131], v[248:251], v[104:107]
	ds_read_b128 v[248:251], v218 offset:53248
	s_waitcnt lgkmcnt(3)
	v_pk_mul_f32 v[110:111], v[110:111], v[122:123]
	s_nop 0
	v_pk_mul_f32 v[114:115], v[114:115], v[134:135]
	v_pk_mul_f32 v[112:113], v[112:113], v[132:133]
	v_pk_mul_f32 v[108:109], v[108:109], v[120:121]
	ds_read_b128 v[120:123], v201
	s_waitcnt lgkmcnt(3)
	v_pk_mul_f32 v[118:119], v[118:119], v[126:127]
	v_pk_mul_f32 v[116:117], v[116:117], v[124:125]
	ds_read_b128 v[124:127], v201 offset:16
	ds_read_b128 v[132:135], v202
	s_waitcnt lgkmcnt(4)
	v_pk_mul_f32 v[130:131], v[106:107], v[242:243]
	v_pk_mul_f32 v[128:129], v[104:105], v[240:241]
	ds_read_b128 v[238:241], v202 offset:16
	s_waitcnt lgkmcnt(4)
	v_lshlrev_b32_e32 v139, 16, v248
	v_and_b32_e32 v170, 0xffff0000, v248
	v_lshlrev_b32_e32 v237, 16, v249
	v_and_b32_e32 v242, 0xffff0000, v249
	v_lshlrev_b32_e32 v243, 16, v250
	v_and_b32_e32 v244, 0xffff0000, v250
	v_lshlrev_b32_e32 v245, 16, v251
	v_and_b32_e32 v246, 0xffff0000, v251
	s_waitcnt lgkmcnt(2)
	v_mul_f32_e32 v122, v122, v237
	v_mul_f32_e32 v124, v124, v243
	v_mul_f32_e32 v125, v125, v244
	v_mul_f32_e32 v126, v126, v245
	v_mul_f32_e32 v127, v127, v246
	s_waitcnt lgkmcnt(1)
	v_mul_f32_e32 v237, v134, v237
	v_mul_f32_e32 v123, v123, v242
	v_mul_f32_e32 v242, v135, v242
	v_cvt_pk_bf16_f32 v134, v124, v125
	v_cvt_pk_bf16_f32 v135, v126, v127
	ds_read_b128 v[124:127], v219 offset:53248
	v_mul_f32_e32 v120, v120, v139
	v_mul_f32_e32 v139, v132, v139
	s_waitcnt lgkmcnt(1)
	v_mul_f32_e32 v238, v238, v243
	v_mul_f32_e32 v121, v121, v170
	v_mul_f32_e32 v170, v133, v170
	v_mul_f32_e32 v239, v239, v244
	v_mul_f32_e32 v240, v240, v245
	v_mul_f32_e32 v241, v241, v246
	v_cvt_pk_bf16_f32 v132, v120, v121
	v_cvt_pk_bf16_f32 v133, v122, v123
	v_cvt_pk_bf16_f32 v104, v139, v170
	v_cvt_pk_bf16_f32 v105, v237, v242
	v_cvt_pk_bf16_f32 v106, v238, v239
	v_cvt_pk_bf16_f32 v107, v240, v241
	s_waitcnt lgkmcnt(0)
	v_lshlrev_b32_e32 v139, 16, v124
	v_and_b32_e32 v170, 0xffff0000, v124
	v_lshlrev_b32_e32 v237, 16, v125
	v_and_b32_e32 v250, 0xffff0000, v125
	v_lshlrev_b32_e32 v251, 16, v126
	v_and_b32_e32 v252, 0xffff0000, v126
	v_lshlrev_b32_e32 v253, 16, v127
	v_and_b32_e32 v182, 0xffff0000, v127
	ds_read_b128 v[124:127], v201 offset:128
	ds_read_b128 v[238:241], v201 offset:144
	ds_read_b128 v[242:245], v202 offset:128
	ds_read_b128 v[246:249], v202 offset:144
	s_waitcnt lgkmcnt(0)
	s_barrier
; __device__ __forceinline__ void phase_ssd(const Params& p, uchar* sm, int j, bf16_t* zx, const float* dtraw, float* ssqb) {
;     ...
;                 __syncthreads();
; #pragma unroll
;                 for (int ks = 0; ks < 2; ++ks)
; #pragma unroll
;                     for (int m = 0; m < 4; ++m) {
;                         if (ks == 1 && m < 2) continue;
;                         const bf16x8 afr = *(const bf16x8*)(sm + LDS_MM + (rl * 64 + m * 16 + l15) * RS_T + (ks * 32 + quad * 8) * 2);
;                         yacc[m] = __builtin_amdgcn_mfma_f32_16x16x32_bf16(afr, xdt[ks], yacc[m], 0, 0, 0);
;                     }
;                 const float dec = e1L[rl * 64 + 63];
; #pragma unroll
;                 for (int n = 0; n < 8; ++n) {
;                     st[n] *= dec;
; #pragma unroll
;                     for (int ks = 0; ks < 2; ++ks) { const bf16x8 afr = *(const bf16x8*)(sm + L_BT + (n * 16 + l15) * RS_T + (((ks * 16 + quad * 4) ^ (4 * n)) * 4));
;                         st[n] = __builtin_amdgcn_mfma_f32_16x16x32_bf16(afr, xdd[ks], st[n], 0, 0, 0); }
;                 }
;             }
;             if (c + 1 < 32) { load_raw(zc + 64 * LDZ + 2048 + colb, toff, false, 2 * lp, rb); load_raw(zc + 64 * LDZ + 2048 + colc, toff, false, 2 * lp, rc); }
	ds_read_b128 v[120:123], v220
	s_waitcnt lgkmcnt(0)
	v_mfma_f32_16x16x32_bf16 v[108:111], v[120:123], v[132:135], v[108:111]
	ds_read_b128 v[120:123], v220 offset:2304
	v_mul_f32_e32 v241, v241, v182
	v_mul_f32_e32 v124, v124, v139
	s_waitcnt lgkmcnt(0)
	v_mfma_f32_16x16x32_bf16 v[112:115], v[120:123], v[132:135], v[112:115]
	ds_read_b128 v[120:123], v220 offset:4608
	v_mul_f32_e32 v144, v238, v251
	v_mul_f32_e32 v139, v242, v139
	s_waitcnt lgkmcnt(0)
	v_mfma_f32_16x16x32_bf16 v[116:119], v[120:123], v[132:135], v[116:119]
	ds_read_b128 v[120:123], v220 offset:6912
	v_mul_f32_e32 v145, v246, v251
	v_mul_f32_e32 v125, v125, v170
	s_waitcnt lgkmcnt(0)
	v_mfma_f32_16x16x32_bf16 v[128:131], v[120:123], v[132:135], v[128:131]
	ds_read_b128 v[120:123], v220 offset:4672
	v_mul_f32_e32 v242, v239, v252
	v_mul_f32_e32 v126, v126, v237
	v_mul_f32_e32 v246, v240, v253
	v_mul_f32_e32 v127, v127, v250
	v_cvt_pk_bf16_f32 v238, v124, v125
	v_cvt_pk_bf16_f32 v239, v126, v127
	v_cvt_pk_bf16_f32 v240, v144, v242
	v_cvt_pk_bf16_f32 v241, v246, v241
	v_mul_f32_e32 v170, v243, v170
	s_waitcnt lgkmcnt(0)
	v_mfma_f32_16x16x32_bf16 v[120:123], v[120:123], v[238:241], v[116:119]
	ds_read_b128 v[116:119], v220 offset:6976
	v_mul_f32_e32 v243, v247, v252
	v_mul_f32_e32 v237, v244, v237
	v_mul_f32_e32 v244, v248, v253
	s_waitcnt lgkmcnt(0)
	v_mfma_f32_16x16x32_bf16 v[116:119], v[116:119], v[238:241], v[128:131]
	ds_read_b32 v128, v203
	s_nop 2
	v_mul_f32_e32 v245, v245, v250
	v_mul_f32_e32 v182, v249, v182
	v_cvt_pk_bf16_f32 v124, v139, v170
	v_cvt_pk_bf16_f32 v125, v237, v245
	s_waitcnt lgkmcnt(0)
	v_pk_mul_f32 v[74:75], v[74:75], v[128:129] op_sel_hi:[1,0]
	v_pk_mul_f32 v[72:73], v[72:73], v[128:129] op_sel_hi:[1,0]
	v_add_u32_e32 v129, v205, v188
	ds_read_b128 v[130:133], v129 offset:34816
	ds_read_b128 v[238:241], v129 offset:34880
	ds_read_b128 v[246:249], v221 offset:37120
	ds_read_b128 v[250:253], v221 offset:37184
	s_waitcnt lgkmcnt(3)
	v_mfma_f32_16x16x32_bf16 v[72:75], v[130:133], v[104:107], v[72:75]
	ds_read_b128 v[130:133], v222 offset:39424
	v_cvt_pk_bf16_f32 v126, v145, v243
	v_cvt_pk_bf16_f32 v127, v244, v182
	ds_read_b128 v[242:245], v222 offset:39488
	v_pk_mul_f32 v[78:79], v[78:79], v[128:129] op_sel_hi:[1,0]
	s_waitcnt lgkmcnt(4)
	v_mfma_f32_16x16x32_bf16 v[72:75], v[238:241], v[124:127], v[72:75]
	ds_read_b128 v[238:241], v223 offset:41728
	v_pk_mul_f32 v[76:77], v[76:77], v[128:129] op_sel_hi:[1,0]
	v_pk_mul_f32 v[66:67], v[66:67], v[128:129] op_sel_hi:[1,0]
	v_pk_mul_f32 v[64:65], v[64:65], v[128:129] op_sel_hi:[1,0]
	s_waitcnt lgkmcnt(4)
	v_mfma_f32_16x16x32_bf16 v[76:79], v[246:249], v[104:107], v[76:79]
	ds_read_b128 v[246:249], v223 offset:41792
	v_pk_mul_f32 v[70:71], v[70:71], v[128:129] op_sel_hi:[1,0]
	v_pk_mul_f32 v[68:69], v[68:69], v[128:129] op_sel_hi:[1,0]
	s_waitcnt lgkmcnt(4)
	v_mfma_f32_16x16x32_bf16 v[76:79], v[250:253], v[124:127], v[76:79]
	ds_read_b128 v[250:253], v129 offset:44096
	v_pk_mul_f32 v[94:95], v[94:95], v[128:129] op_sel_hi:[1,0]
	v_pk_mul_f32 v[92:93], v[92:93], v[128:129] op_sel_hi:[1,0]
	s_waitcnt lgkmcnt(4)
	v_mfma_f32_16x16x32_bf16 v[64:67], v[130:133], v[104:107], v[64:67]
	ds_read_b128 v[130:133], v129 offset:44032
	v_pk_mul_f32 v[82:83], v[82:83], v[128:129] op_sel_hi:[1,0]
	v_pk_mul_f32 v[80:81], v[80:81], v[128:129] op_sel_hi:[1,0]
	s_waitcnt lgkmcnt(4)
	v_mfma_f32_16x16x32_bf16 v[64:67], v[242:245], v[124:127], v[64:67]
	ds_read_b128 v[242:245], v221 offset:46400
	v_pk_mul_f32 v[86:87], v[86:87], v[128:129] op_sel_hi:[1,0]
	v_pk_mul_f32 v[84:85], v[84:85], v[128:129] op_sel_hi:[1,0]
	s_waitcnt lgkmcnt(4)
	v_mfma_f32_16x16x32_bf16 v[68:71], v[238:241], v[104:107], v[68:71]
	ds_read_b128 v[238:241], v221 offset:46336
	v_pk_mul_f32 v[90:91], v[90:91], v[128:129] op_sel_hi:[1,0]
	v_pk_mul_f32 v[88:89], v[88:89], v[128:129] op_sel_hi:[1,0]
	s_waitcnt lgkmcnt(4)
	v_mfma_f32_16x16x32_bf16 v[68:71], v[246:249], v[124:127], v[68:71]
	ds_read_b128 v[246:249], v222 offset:48704
	s_waitcnt lgkmcnt(4)
	v_mfma_f32_16x16x32_bf16 v[92:95], v[250:253], v[104:107], v[92:95]
	ds_read_b128 v[250:253], v222 offset:48640
	s_waitcnt lgkmcnt(4)
	v_mfma_f32_16x16x32_bf16 v[92:95], v[130:133], v[124:127], v[92:95]
	ds_read_b128 v[128:131], v223 offset:51008
	s_waitcnt lgkmcnt(3)
	v_mfma_f32_16x16x32_bf16 v[80:83], v[242:245], v[104:107], v[80:83]
	v_mfma_f32_16x16x32_bf16 v[80:83], v[238:241], v[124:127], v[80:83]
	ds_read_b128 v[240:243], v223 offset:50944
	s_waitcnt lgkmcnt(1)
	v_mfma_f32_16x16x32_bf16 v[84:87], v[246:249], v[104:107], v[84:87]
	v_mfma_f32_16x16x32_bf16 v[84:87], v[250:253], v[124:127], v[84:87]
	v_mfma_f32_16x16x32_bf16 v[88:91], v[128:131], v[104:107], v[88:91]
	s_waitcnt lgkmcnt(0)
	v_mfma_f32_16x16x32_bf16 v[88:91], v[240:243], v[124:127], v[88:91]
	s_cbranch_vccnz .Lssd_drain
	v_lshl_add_u64 v[40:41], s[66:67], 0, v[176:177]
	s_mov_b64 vcc, 0x64d6000
	v_lshl_add_u64 v[20:21], v[40:41], 0, vcc
	s_mov_b64 vcc, 0x64d9000
	v_lshl_add_u64 v[28:29], v[40:41], 0, vcc
	s_mov_b64 vcc, 0x64dc000
	v_lshl_add_u64 v[32:33], v[40:41], 0, vcc
	global_load_dwordx4 v[20:23], v[20:21], off offset:3712
	s_nop 0
	global_load_dwordx4 v[28:31], v[28:29], off offset:3840
	s_mov_b64 vcc, 0x64e0000
	v_lshl_add_u64 v[44:45], v[40:41], 0, vcc
	s_mov_b64 vcc, 0x64e3000
	v_lshl_add_u64 v[60:61], v[40:41], 0, vcc
	global_load_dwordx4 v[32:35], v[32:33], off offset:3968
	s_nop 0
	global_load_dwordx4 v[36:39], v[44:45], off
	s_mov_b64 vcc, 0x64d7000
	v_lshl_add_u64 v[46:47], v[40:41], 0, vcc
	s_mov_b64 vcc, 0x64da000
	v_lshl_add_u64 v[42:43], v[40:41], 0, vcc
	s_mov_b64 vcc, 0x64dd000
	v_lshl_add_u64 v[40:41], v[40:41], 0, vcc
	global_load_dwordx4 v[48:51], v[42:43], off offset:1792
	global_load_dwordx4 v[52:55], v[40:41], off offset:1920
	s_nop 0
	global_load_dwordx4 v[40:43], v[60:61], off offset:128
	global_load_dwordx4 v[56:59], v[44:45], off offset:2048
	s_nop 0
	global_load_dwordx4 v[44:47], v[46:47], off offset:1664
	s_nop 0
	global_load_dwordx4 v[60:63], v[60:61], off offset:2176
; __device__ __forceinline__ void phase_ssd(const Params& p, uchar* sm, int j, bf16_t* zx, const float* dtraw, float* ssqb) {
;     ...
;             __syncthreads();
; #pragma unroll
;             for (int m = 0; m < 4; ++m)
; #pragma unroll
;                 for (int r = 0; r < 4; ++r) *(float*)(sm + (m * 16 + quad * 4 + r) * RS_Y + (chl + l15) * 4) = yacc[m][r];
;             __syncthreads();
.LBB0_479:
	v_add_u32_e32 v104, 0x400, v224
	s_barrier
	ds_write2_b32 v104, v110, v111 offset0:8 offset1:140
	v_add_u32_e32 v104, 0x2000, v224
	ds_write2_b32 v104, v112, v113 offset0:64 offset1:196
	v_add_u32_e32 v104, 0x2400, v224
	ds_write2_b32 v104, v114, v115 offset0:72 offset1:204
	v_add_u32_e32 v104, 0x4200, v224
	ds_write2_b32 v104, v120, v121 offset1:132
	v_add_u32_e32 v104, 0x4600, v224
	ds_write2_b32 v104, v122, v123 offset0:8 offset1:140
	v_add_u32_e32 v104, 0x6200, v224
	ds_write2_b32 v104, v116, v117 offset0:64 offset1:196
	v_add_u32_e32 v104, 0x6600, v224
	s_waitcnt vmcnt(11)
	ds_write2_b32 v104, v118, v119 offset0:72 offset1:204
	ds_write2_b32 v224, v108, v109 offset1:132
	s_waitcnt lgkmcnt(0)
	s_barrier
; __device__ __forceinline__ u32x4 pack8(const float (&o)[8]) { u32x4 r; r.x = pk2(o[0], o[1]); r.y = pk2(o[2], o[3]); r.z = pk2(o[4], o[5]); r.w = pk2(o[6], o[7]); return r; }
; __device__ __forceinline__ float silu_f(float v) { return v * __builtin_amdgcn_rcpf(1.f + __expf(-v)); }
; __device__ __forceinline__ void phase_ssd(const Params& p, uchar* sm, int j, bf16_t* zx, const float* dtraw, float* ssqb) {
;     ...
;             {
;                 float zf[8], o[8], xf[8];
;                 const f32x4 y0 = *(const f32x4*)(sm + (2 * lp) * RS_Y + c8 * 32), y1 = *(const f32x4*)(sm + (2 * lp) * RS_Y + c8 * 32 + 16);
;                 unpack8(z0, zf); unpack8(xp0, xf);
; #pragma unroll
;                 for (int i = 0; i < 4; ++i) { o[i] = (y0[i] + dskip * xf[i]) * silu_f(zf[i]); o[4 + i] = (y1[i] + dskip * xf[4 + i]) * silu_f(zf[4 + i]); }
;                 *(u32x4*)(zc + colx + toff) = pack8(o);
;                 float q0 = 0.f;
; #pragma unroll
;                 for (int i = 0; i < 8; ++i) q0 += o[i] * o[i];
;                 const f32x4 y2 = *(const f32x4*)(sm + (2 * lp + 1) * RS_Y + c8 * 32), y3 = *(const f32x4*)(sm + (2 * lp + 1) * RS_Y + c8 * 32 + 16);
;                 unpack8(z1, zf); unpack8(xp1, xf);
; #pragma unroll
;                 for (int i = 0; i < 4; ++i) { o[i] = (y2[i] + dskip * xf[i]) * silu_f(zf[i]); o[4 + i] = (y3[i] + dskip * xf[4 + i]) * silu_f(zf[4 + i]); }
;                 *(u32x4*)(zc + colx + LDZ + toff) = pack8(o);
;                 float q1 = 0.f;
; #pragma unroll
;                 for (int i = 0; i < 8; ++i) q1 += o[i] * o[i];
; #pragma unroll
;                 for (int sft = 1; sft < 16; sft <<= 1) { q0 += __shfl_xor(q0, sft); q1 += __shfl_xor(q1, sft); }
;                 if (c8 == 0) { float* sq = ssqb + (size_t)(zrow0 + 2 * lp) * 16 + g * 2 + hp; sq[0] = q0; sq[16] = q1; }
	ds_read_b128 v[104:107], v225
	ds_read_b128 v[108:111], v225 offset:16
	ds_read_b128 v[124:127], v226
	ds_read_b128 v[128:131], v226 offset:16
	v_lshlrev_b32_e32 v132, 16, v100
	v_and_b32_e32 v133, 0xffff0000, v100
	v_lshlrev_b32_e32 v134, 16, v101
	v_and_b32_e32 v135, 0xffff0000, v101
	v_lshlrev_b32_e32 v238, 16, v102
	v_and_b32_e32 v239, 0xffff0000, v102
	v_lshlrev_b32_e32 v240, 16, v103
	v_and_b32_e32 v241, 0xffff0000, v103
	v_pk_mul_f32 v[112:113], v[132:133], s[98:99]
	v_pk_mul_f32 v[114:115], v[134:135], s[98:99]
	v_pk_mul_f32 v[116:117], v[238:239], s[98:99]
	v_pk_mul_f32 v[118:119], v[240:241], s[98:99]
	v_exp_f32_e32 v112, v112
	v_exp_f32_e32 v113, v113
	v_exp_f32_e32 v114, v114
	v_exp_f32_e32 v115, v115
	v_exp_f32_e32 v116, v116
	v_exp_f32_e32 v117, v117
	v_exp_f32_e32 v118, v118
	v_exp_f32_e32 v119, v119
	v_pk_add_f32 v[112:113], v[112:113], s[100:101]
	v_pk_add_f32 v[114:115], v[114:115], s[100:101]
	v_pk_add_f32 v[116:117], v[116:117], s[100:101]
	v_pk_add_f32 v[118:119], v[118:119], s[100:101]
	v_rcp_f32_e32 v112, v112
	v_rcp_f32_e32 v113, v113
	v_rcp_f32_e32 v114, v114
	v_rcp_f32_e32 v115, v115
	v_rcp_f32_e32 v116, v116
	v_rcp_f32_e32 v117, v117
	v_rcp_f32_e32 v118, v118
	v_rcp_f32_e32 v119, v119
	v_pk_mul_f32 v[112:113], v[112:113], v[132:133]
	v_pk_mul_f32 v[114:115], v[114:115], v[134:135]
	v_pk_mul_f32 v[116:117], v[116:117], v[238:239]
	v_pk_mul_f32 v[118:119], v[118:119], v[240:241]
	v_lshlrev_b32_e32 v132, 16, v235
	v_and_b32_e32 v133, 0xffff0000, v235
	v_lshlrev_b32_e32 v134, 16, v233
	v_and_b32_e32 v135, 0xffff0000, v233
	v_lshlrev_b32_e32 v238, 16, v236
	v_and_b32_e32 v239, 0xffff0000, v236
	v_lshlrev_b32_e32 v240, 16, v234
	v_and_b32_e32 v241, 0xffff0000, v234
	v_pk_mul_f32 v[132:133], v[132:133], v[170:171] op_sel:[0,1] op_sel_hi:[1,1]
	v_pk_mul_f32 v[134:135], v[134:135], v[170:171] op_sel:[0,1] op_sel_hi:[1,1]
	v_pk_mul_f32 v[238:239], v[238:239], v[170:171] op_sel:[0,1] op_sel_hi:[1,1]
	v_pk_mul_f32 v[240:241], v[240:241], v[170:171] op_sel:[0,1] op_sel_hi:[1,1]
	s_waitcnt lgkmcnt(2)
	v_pk_add_f32 v[132:133], v[132:133], v[104:105]
	v_pk_add_f32 v[134:135], v[134:135], v[106:107]
	v_pk_add_f32 v[238:239], v[238:239], v[108:109]
	v_pk_add_f32 v[240:241], v[240:241], v[110:111]
	v_pk_mul_f32 v[112:113], v[112:113], v[132:133]
	v_pk_mul_f32 v[114:115], v[114:115], v[134:135]
	v_pk_mul_f32 v[116:117], v[116:117], v[238:239]
	v_pk_mul_f32 v[118:119], v[118:119], v[240:241]
	v_mul_f32_e32 v120, v113, v113
	v_fmac_f32_e32 v120, v112, v112
	v_fmac_f32_e32 v120, v114, v114
	v_fmac_f32_e32 v120, v115, v115
	v_fmac_f32_e32 v120, v116, v116
	v_fmac_f32_e32 v120, v117, v117
	v_fmac_f32_e32 v120, v118, v118
	v_fmac_f32_e32 v120, v119, v119
	s_waitcnt vmcnt(10)
	v_lshlrev_b32_e32 v242, 16, v96
	v_and_b32_e32 v243, 0xffff0000, v96
	v_lshlrev_b32_e32 v246, 16, v97
	v_and_b32_e32 v247, 0xffff0000, v97
	v_lshlrev_b32_e32 v248, 16, v98
	v_and_b32_e32 v249, 0xffff0000, v98
	v_lshlrev_b32_e32 v250, 16, v99
	v_and_b32_e32 v251, 0xffff0000, v99
	v_pk_mul_f32 v[104:105], v[242:243], s[98:99]
	v_pk_mul_f32 v[106:107], v[246:247], s[98:99]
	v_pk_mul_f32 v[108:109], v[248:249], s[98:99]
	v_pk_mul_f32 v[110:111], v[250:251], s[98:99]
	v_exp_f32_e32 v104, v104
	v_exp_f32_e32 v105, v105
	v_exp_f32_e32 v106, v106
	v_exp_f32_e32 v107, v107
	v_exp_f32_e32 v108, v108
	v_exp_f32_e32 v109, v109
	v_exp_f32_e32 v110, v110
	v_exp_f32_e32 v111, v111
	v_pk_add_f32 v[104:105], v[104:105], s[100:101]
	v_pk_add_f32 v[106:107], v[106:107], s[100:101]
	v_pk_add_f32 v[108:109], v[108:109], s[100:101]
	v_pk_add_f32 v[110:111], v[110:111], s[100:101]
	v_rcp_f32_e32 v104, v104
	v_rcp_f32_e32 v105, v105
	v_rcp_f32_e32 v106, v106
	v_rcp_f32_e32 v107, v107
	v_rcp_f32_e32 v108, v108
	v_rcp_f32_e32 v109, v109
	v_rcp_f32_e32 v110, v110
	v_rcp_f32_e32 v111, v111
	v_pk_mul_f32 v[104:105], v[104:105], v[242:243]
	v_pk_mul_f32 v[106:107], v[106:107], v[246:247]
	v_pk_mul_f32 v[108:109], v[108:109], v[248:249]
	v_pk_mul_f32 v[110:111], v[110:111], v[250:251]
	v_lshlrev_b32_e32 v242, 16, v231
	v_and_b32_e32 v243, 0xffff0000, v231
	v_lshlrev_b32_e32 v246, 16, v229
	v_and_b32_e32 v247, 0xffff0000, v229
	v_lshlrev_b32_e32 v248, 16, v232
	v_and_b32_e32 v249, 0xffff0000, v232
	v_lshlrev_b32_e32 v250, 16, v230
	v_and_b32_e32 v251, 0xffff0000, v230
	v_pk_mul_f32 v[242:243], v[242:243], v[170:171] op_sel:[0,1] op_sel_hi:[1,1]
	v_pk_mul_f32 v[246:247], v[246:247], v[170:171] op_sel:[0,1] op_sel_hi:[1,1]
	v_pk_mul_f32 v[248:249], v[248:249], v[170:171] op_sel:[0,1] op_sel_hi:[1,1]
	v_pk_mul_f32 v[250:251], v[250:251], v[170:171] op_sel:[0,1] op_sel_hi:[1,1]
	s_waitcnt lgkmcnt(0)
	v_pk_add_f32 v[242:243], v[242:243], v[124:125]
	v_pk_add_f32 v[246:247], v[246:247], v[126:127]
	v_pk_add_f32 v[248:249], v[248:249], v[128:129]
	v_pk_add_f32 v[250:251], v[250:251], v[130:131]
	v_pk_mul_f32 v[104:105], v[104:105], v[242:243]
	v_pk_mul_f32 v[106:107], v[106:107], v[246:247]
	v_pk_mul_f32 v[108:109], v[108:109], v[248:249]
	v_pk_mul_f32 v[110:111], v[110:111], v[250:251]
	v_mul_f32_e32 v121, v105, v105
	v_fmac_f32_e32 v121, v104, v104
	v_fmac_f32_e32 v121, v106, v106
	v_fmac_f32_e32 v121, v107, v107
	v_fmac_f32_e32 v121, v108, v108
	v_fmac_f32_e32 v121, v109, v109
	v_fmac_f32_e32 v121, v110, v110
	v_fmac_f32_e32 v121, v111, v111
	v_cvt_pk_bf16_f32 v98, v116, v117
	v_cvt_pk_bf16_f32 v97, v114, v115
	v_add_f32_dpp v120, v120, v120 quad_perm:[1,0,3,2] row_mask:0xf bank_mask:0xf
	v_add_f32_dpp v121, v121, v121 quad_perm:[1,0,3,2] row_mask:0xf bank_mask:0xf
	v_cvt_pk_bf16_f32 v96, v112, v113
	v_cvt_pk_bf16_f32 v99, v118, v119
	v_add_f32_dpp v120, v120, v120 quad_perm:[2,3,0,1] row_mask:0xf bank_mask:0xf
	v_add_f32_dpp v121, v121, v121 quad_perm:[2,3,0,1] row_mask:0xf bank_mask:0xf
	global_store_dwordx4 v[180:181], v[96:99], off
	v_cvt_pk_bf16_f32 v100, v104, v105
	v_cvt_pk_bf16_f32 v101, v106, v107
	v_add_f32_dpp v120, v120, v120 row_half_mirror row_mask:0xf bank_mask:0xf
	v_add_f32_dpp v121, v121, v121 row_half_mirror row_mask:0xf bank_mask:0xf
	v_cvt_pk_bf16_f32 v102, v108, v109
	v_cvt_pk_bf16_f32 v103, v110, v111
	v_add_f32_dpp v120, v120, v120 row_mirror row_mask:0xf bank_mask:0xf
	v_add_f32_dpp v121, v121, v121 row_mirror row_mask:0xf bank_mask:0xf
	global_store_dwordx4 v[178:179], v[100:103], off
	s_and_saveexec_b64 s[0:1], s[24:25]
	s_cbranch_execz .LBB0_465
	v_lshl_add_u64 v[96:97], s[66:67], 0, v[172:173]
	s_mov_b64 vcc, 0x1ec1c000
	v_lshl_add_u64 v[96:97], v[96:97], 0, vcc
	global_store_dword v[96:97], v120, off
	global_store_dword v[96:97], v121, off offset:64
	s_branch .LBB0_465
